# speedup vs baseline: 1.0105x; 1.0105x over previous
; __device__ __forceinline__ int tid_op() { int t = threadIdx.x & 255; asm volatile("" : "+v"(t)); return t; }
; __device__ __forceinline__ int vb_op() { return (int)(blockIdx.x << 1) | sub_op(); }
; __device__ void ssd_scan_phase(const Params& p) {
;   const int nthr = p.nblk * 256;
;   for (int s = vb_op() * 256 + tid_op(); s < 131072; s += nthr) {
;     const int n2 = s & 63, pp = (s >> 6) & 63, h = (s >> 12) & 15, b = s >> 16;
;     const size_t off = (size_t)h * 8192 + pp * 128 + n2 * 2;
;     float c0 = 0.f, c1 = 0.f;
; #pragma unroll 8
;     for (int c = 0; c < 128; ++c) {
;       const size_t o = (size_t)(b * 128 + c) * 131072 + off;
;       const float2 st = *(const float2*)(p.states + o);
;       const float dec = p.cdecay[(b * 128 + c) * 16 + h];
;       *(u32*)(p.prev + o) = pack2(c0, c1);
;       c0 = c0 * dec + st.x;
;       c1 = c1 * dec + st.y;
;     }
;   }
; }
.LBB0_393:
	s_mov_b32 s96, 0xffc80000
	s_mov_b32 s97, -1
	v_lshl_add_u64 v[2:3], v[2:3], 0, s[96:97]
	s_mov_b32 s96, 0xffe40000
	v_lshl_add_u64 v[0:1], v[0:1], 0, s[96:97]
	v_ashrrev_i32_e32 v9, 31, v8
	v_lshl_add_u64 v[10:11], v[8:9], 2, s[42:43]
	s_mov_b64 s[98:99], 0x80000
	s_mov_b64 s[100:101], 0x40000
	s_mov_b64 s[96:97], 0x400
	v_lshl_add_u64 v[32:33], v[2:3], 0, 0
	v_lshl_add_u64 v[34:35], v[32:33], 0, s[98:99]
	v_lshl_add_u64 v[36:37], v[34:35], 0, s[98:99]
	v_lshl_add_u64 v[38:39], v[36:37], 0, s[98:99]
	v_lshl_add_u64 v[40:41], v[38:39], 0, s[98:99]
	v_lshl_add_u64 v[42:43], v[40:41], 0, s[98:99]
	v_lshl_add_u64 v[44:45], v[42:43], 0, s[98:99]
	v_lshl_add_u64 v[46:47], v[44:45], 0, s[98:99]
	v_lshl_add_u64 v[48:49], v[46:47], 0, s[98:99]
	v_lshl_add_u64 v[50:51], v[48:49], 0, s[98:99]
	v_lshl_add_u64 v[52:53], v[50:51], 0, s[98:99]
	v_lshl_add_u64 v[54:55], v[52:53], 0, s[98:99]
	v_lshl_add_u64 v[56:57], v[54:55], 0, s[98:99]
	v_lshl_add_u64 v[58:59], v[56:57], 0, s[98:99]
	v_lshl_add_u64 v[60:61], v[58:59], 0, s[98:99]
	v_lshl_add_u64 v[62:63], v[60:61], 0, s[98:99]
	global_load_dwordx2 v[64:65], v[32:33], off
	global_load_dwordx2 v[66:67], v[34:35], off
	global_load_dwordx2 v[68:69], v[36:37], off
	global_load_dwordx2 v[70:71], v[38:39], off
	global_load_dwordx2 v[72:73], v[40:41], off
	global_load_dwordx2 v[74:75], v[42:43], off
	global_load_dwordx2 v[76:77], v[44:45], off
	global_load_dwordx2 v[78:79], v[46:47], off
	global_load_dwordx2 v[80:81], v[48:49], off
	global_load_dwordx2 v[82:83], v[50:51], off
	global_load_dwordx2 v[84:85], v[52:53], off
	global_load_dwordx2 v[86:87], v[54:55], off
	global_load_dwordx2 v[88:89], v[56:57], off
	global_load_dwordx2 v[90:91], v[58:59], off
	global_load_dwordx2 v[92:93], v[60:61], off
	global_load_dwordx2 v[94:95], v[62:63], off
	global_load_dword v96, v[10:11], off
	global_load_dword v98, v[10:11], off offset:64
	global_load_dword v100, v[10:11], off offset:128
	global_load_dword v102, v[10:11], off offset:192
	global_load_dword v104, v[10:11], off offset:256
	global_load_dword v106, v[10:11], off offset:320
	global_load_dword v108, v[10:11], off offset:384
	global_load_dword v110, v[10:11], off offset:448
	global_load_dword v112, v[10:11], off offset:512
	global_load_dword v114, v[10:11], off offset:576
	global_load_dword v116, v[10:11], off offset:640
	global_load_dword v118, v[10:11], off offset:704
	global_load_dword v120, v[10:11], off offset:768
	global_load_dword v122, v[10:11], off offset:832
	global_load_dword v124, v[10:11], off offset:896
	global_load_dword v126, v[10:11], off offset:960
	v_lshl_add_u64 v[2:3], v[2:3], 0, s[10:11]
	v_lshl_add_u64 v[2:3], v[2:3], 0, s[10:11]
	v_lshl_add_u64 v[10:11], v[10:11], 0, s[96:97]
.Lscan_loop:
	v_lshl_add_u64 v[32:33], v[2:3], 0, 0
	v_lshl_add_u64 v[34:35], v[32:33], 0, s[98:99]
	v_lshl_add_u64 v[36:37], v[34:35], 0, s[98:99]
	v_lshl_add_u64 v[38:39], v[36:37], 0, s[98:99]
	v_lshl_add_u64 v[40:41], v[38:39], 0, s[98:99]
	v_lshl_add_u64 v[42:43], v[40:41], 0, s[98:99]
	v_lshl_add_u64 v[44:45], v[42:43], 0, s[98:99]
	v_lshl_add_u64 v[46:47], v[44:45], 0, s[98:99]
	v_lshl_add_u64 v[48:49], v[46:47], 0, s[98:99]
	v_lshl_add_u64 v[50:51], v[48:49], 0, s[98:99]
	v_lshl_add_u64 v[52:53], v[50:51], 0, s[98:99]
	v_lshl_add_u64 v[54:55], v[52:53], 0, s[98:99]
	v_lshl_add_u64 v[56:57], v[54:55], 0, s[98:99]
	v_lshl_add_u64 v[58:59], v[56:57], 0, s[98:99]
	v_lshl_add_u64 v[60:61], v[58:59], 0, s[98:99]
	v_lshl_add_u64 v[62:63], v[60:61], 0, s[98:99]
	global_load_dwordx2 v[168:169], v[32:33], off
	global_load_dwordx2 v[170:171], v[34:35], off
	global_load_dwordx2 v[172:173], v[36:37], off
	global_load_dwordx2 v[174:175], v[38:39], off
	global_load_dwordx2 v[176:177], v[40:41], off
	global_load_dwordx2 v[178:179], v[42:43], off
	global_load_dwordx2 v[180:181], v[44:45], off
	global_load_dwordx2 v[182:183], v[46:47], off
	global_load_dwordx2 v[184:185], v[48:49], off
	global_load_dwordx2 v[186:187], v[50:51], off
	global_load_dwordx2 v[188:189], v[52:53], off
	global_load_dwordx2 v[190:191], v[54:55], off
	global_load_dwordx2 v[192:193], v[56:57], off
	global_load_dwordx2 v[194:195], v[58:59], off
	global_load_dwordx2 v[196:197], v[60:61], off
	global_load_dwordx2 v[198:199], v[62:63], off
	global_load_dword v200, v[10:11], off
	global_load_dword v202, v[10:11], off offset:64
	global_load_dword v204, v[10:11], off offset:128
	global_load_dword v206, v[10:11], off offset:192
	global_load_dword v208, v[10:11], off offset:256
	global_load_dword v210, v[10:11], off offset:320
	global_load_dword v212, v[10:11], off offset:384
	global_load_dword v214, v[10:11], off offset:448
	global_load_dword v216, v[10:11], off offset:512
	global_load_dword v218, v[10:11], off offset:576
	global_load_dword v220, v[10:11], off offset:640
	global_load_dword v222, v[10:11], off offset:704
	global_load_dword v224, v[10:11], off offset:768
	global_load_dword v226, v[10:11], off offset:832
	global_load_dword v228, v[10:11], off offset:896
	global_load_dword v230, v[10:11], off offset:960
	v_lshl_add_u64 v[2:3], v[2:3], 0, s[10:11]
	v_lshl_add_u64 v[2:3], v[2:3], 0, s[10:11]
	v_lshl_add_u64 v[10:11], v[10:11], 0, s[96:97]
	v_lshl_add_u64 v[32:33], v[0:1], 0, 0
	v_lshl_add_u64 v[34:35], v[32:33], 0, s[100:101]
	v_lshl_add_u64 v[36:37], v[34:35], 0, s[100:101]
	v_lshl_add_u64 v[38:39], v[36:37], 0, s[100:101]
	v_lshl_add_u64 v[40:41], v[38:39], 0, s[100:101]
	v_lshl_add_u64 v[42:43], v[40:41], 0, s[100:101]
	v_lshl_add_u64 v[44:45], v[42:43], 0, s[100:101]
	v_lshl_add_u64 v[46:47], v[44:45], 0, s[100:101]
	v_lshl_add_u64 v[48:49], v[46:47], 0, s[100:101]
	v_lshl_add_u64 v[50:51], v[48:49], 0, s[100:101]
	v_lshl_add_u64 v[52:53], v[50:51], 0, s[100:101]
	v_lshl_add_u64 v[54:55], v[52:53], 0, s[100:101]
	v_lshl_add_u64 v[56:57], v[54:55], 0, s[100:101]
	v_lshl_add_u64 v[58:59], v[56:57], 0, s[100:101]
	v_lshl_add_u64 v[60:61], v[58:59], 0, s[100:101]
	v_lshl_add_u64 v[62:63], v[60:61], 0, s[100:101]
	s_waitcnt vmcnt(47)
; __device__ __forceinline__ int tid_op() { int t = threadIdx.x & 255; asm volatile("" : "+v"(t)); return t; }
; __device__ __forceinline__ int vb_op() { return (int)(blockIdx.x << 1) | sub_op(); }
; __device__ void ssd_scan_phase(const Params& p) {
;   const int nthr = p.nblk * 256;
;   for (int s = vb_op() * 256 + tid_op(); s < 131072; s += nthr) {
;     const int n2 = s & 63, pp = (s >> 6) & 63, h = (s >> 12) & 15, b = s >> 16;
;     const size_t off = (size_t)h * 8192 + pp * 128 + n2 * 2;
;     float c0 = 0.f, c1 = 0.f;
; #pragma unroll 8
;     for (int c = 0; c < 128; ++c) {
;       const size_t o = (size_t)(b * 128 + c) * 131072 + off;
;       const float2 st = *(const float2*)(p.states + o);
;       const float dec = p.cdecay[(b * 128 + c) * 16 + h];
;       *(u32*)(p.prev + o) = pack2(c0, c1);
;       c0 = c0 * dec + st.x;
;       c1 = c1 * dec + st.y;
;     }
;   }
; }
	v_cvt_pk_bf16_f32 v12, v4, v5
	global_store_dword v[32:33], v12, off
	v_pk_fma_f32 v[4:5], v[4:5], v[96:97], v[64:65] op_sel_hi:[1,0,1]
	s_nop 0
	s_waitcnt vmcnt(47)
	v_cvt_pk_bf16_f32 v13, v4, v5
	global_store_dword v[34:35], v13, off
	v_pk_fma_f32 v[4:5], v[4:5], v[98:99], v[66:67] op_sel_hi:[1,0,1]
	s_nop 0
	s_waitcnt vmcnt(47)
	v_cvt_pk_bf16_f32 v12, v4, v5
	global_store_dword v[36:37], v12, off
	v_pk_fma_f32 v[4:5], v[4:5], v[100:101], v[68:69] op_sel_hi:[1,0,1]
	s_nop 0
	s_waitcnt vmcnt(47)
	v_cvt_pk_bf16_f32 v13, v4, v5
	global_store_dword v[38:39], v13, off
	v_pk_fma_f32 v[4:5], v[4:5], v[102:103], v[70:71] op_sel_hi:[1,0,1]
	s_nop 0
	s_waitcnt vmcnt(47)
	v_cvt_pk_bf16_f32 v12, v4, v5
	global_store_dword v[40:41], v12, off
	v_pk_fma_f32 v[4:5], v[4:5], v[104:105], v[72:73] op_sel_hi:[1,0,1]
	s_nop 0
	s_waitcnt vmcnt(47)
	v_cvt_pk_bf16_f32 v13, v4, v5
	global_store_dword v[42:43], v13, off
	v_pk_fma_f32 v[4:5], v[4:5], v[106:107], v[74:75] op_sel_hi:[1,0,1]
	s_nop 0
	s_waitcnt vmcnt(47)
	v_cvt_pk_bf16_f32 v12, v4, v5
	global_store_dword v[44:45], v12, off
	v_pk_fma_f32 v[4:5], v[4:5], v[108:109], v[76:77] op_sel_hi:[1,0,1]
	s_nop 0
	s_waitcnt vmcnt(47)
	v_cvt_pk_bf16_f32 v13, v4, v5
	global_store_dword v[46:47], v13, off
	v_pk_fma_f32 v[4:5], v[4:5], v[110:111], v[78:79] op_sel_hi:[1,0,1]
	s_nop 0
	s_waitcnt vmcnt(47)
	v_cvt_pk_bf16_f32 v12, v4, v5
	global_store_dword v[48:49], v12, off
	v_pk_fma_f32 v[4:5], v[4:5], v[112:113], v[80:81] op_sel_hi:[1,0,1]
	s_nop 0
	s_waitcnt vmcnt(47)
	v_cvt_pk_bf16_f32 v13, v4, v5
	global_store_dword v[50:51], v13, off
	v_pk_fma_f32 v[4:5], v[4:5], v[114:115], v[82:83] op_sel_hi:[1,0,1]
	s_nop 0
	s_waitcnt vmcnt(47)
	v_cvt_pk_bf16_f32 v12, v4, v5
	global_store_dword v[52:53], v12, off
	v_pk_fma_f32 v[4:5], v[4:5], v[116:117], v[84:85] op_sel_hi:[1,0,1]
	s_nop 0
	s_waitcnt vmcnt(47)
	v_cvt_pk_bf16_f32 v13, v4, v5
	global_store_dword v[54:55], v13, off
	v_pk_fma_f32 v[4:5], v[4:5], v[118:119], v[86:87] op_sel_hi:[1,0,1]
	s_nop 0
	s_waitcnt vmcnt(47)
	v_cvt_pk_bf16_f32 v12, v4, v5
	global_store_dword v[56:57], v12, off
	v_pk_fma_f32 v[4:5], v[4:5], v[120:121], v[88:89] op_sel_hi:[1,0,1]
	s_nop 0
	s_waitcnt vmcnt(47)
	v_cvt_pk_bf16_f32 v13, v4, v5
	global_store_dword v[58:59], v13, off
	v_pk_fma_f32 v[4:5], v[4:5], v[122:123], v[90:91] op_sel_hi:[1,0,1]
	s_nop 0
	s_waitcnt vmcnt(47)
	v_cvt_pk_bf16_f32 v12, v4, v5
	global_store_dword v[60:61], v12, off
	v_pk_fma_f32 v[4:5], v[4:5], v[124:125], v[92:93] op_sel_hi:[1,0,1]
	s_nop 0
	s_waitcnt vmcnt(47)
	v_cvt_pk_bf16_f32 v13, v4, v5
	global_store_dword v[62:63], v13, off
	v_pk_fma_f32 v[4:5], v[4:5], v[126:127], v[94:95] op_sel_hi:[1,0,1]
	s_nop 0
	v_lshl_add_u64 v[0:1], v[0:1], 0, s[10:11]
	s_addk_i32 s21, 0x200
	s_cmpk_eq_i32 s21, 0x800
	s_cbranch_scc1 .Lscan_last
	v_lshl_add_u64 v[32:33], v[2:3], 0, 0
	v_lshl_add_u64 v[34:35], v[32:33], 0, s[98:99]
	v_lshl_add_u64 v[36:37], v[34:35], 0, s[98:99]
	v_lshl_add_u64 v[38:39], v[36:37], 0, s[98:99]
	v_lshl_add_u64 v[40:41], v[38:39], 0, s[98:99]
	v_lshl_add_u64 v[42:43], v[40:41], 0, s[98:99]
	v_lshl_add_u64 v[44:45], v[42:43], 0, s[98:99]
	v_lshl_add_u64 v[46:47], v[44:45], 0, s[98:99]
	v_lshl_add_u64 v[48:49], v[46:47], 0, s[98:99]
	v_lshl_add_u64 v[50:51], v[48:49], 0, s[98:99]
	v_lshl_add_u64 v[52:53], v[50:51], 0, s[98:99]
	v_lshl_add_u64 v[54:55], v[52:53], 0, s[98:99]
	v_lshl_add_u64 v[56:57], v[54:55], 0, s[98:99]
	v_lshl_add_u64 v[58:59], v[56:57], 0, s[98:99]
	v_lshl_add_u64 v[60:61], v[58:59], 0, s[98:99]
	v_lshl_add_u64 v[62:63], v[60:61], 0, s[98:99]
	global_load_dwordx2 v[64:65], v[32:33], off
	global_load_dwordx2 v[66:67], v[34:35], off
	global_load_dwordx2 v[68:69], v[36:37], off
	global_load_dwordx2 v[70:71], v[38:39], off
	global_load_dwordx2 v[72:73], v[40:41], off
	global_load_dwordx2 v[74:75], v[42:43], off
	global_load_dwordx2 v[76:77], v[44:45], off
	global_load_dwordx2 v[78:79], v[46:47], off
	global_load_dwordx2 v[80:81], v[48:49], off
	global_load_dwordx2 v[82:83], v[50:51], off
	global_load_dwordx2 v[84:85], v[52:53], off
	global_load_dwordx2 v[86:87], v[54:55], off
	global_load_dwordx2 v[88:89], v[56:57], off
	global_load_dwordx2 v[90:91], v[58:59], off
	global_load_dwordx2 v[92:93], v[60:61], off
	global_load_dwordx2 v[94:95], v[62:63], off
	global_load_dword v96, v[10:11], off
	global_load_dword v98, v[10:11], off offset:64
	global_load_dword v100, v[10:11], off offset:128
	global_load_dword v102, v[10:11], off offset:192
	global_load_dword v104, v[10:11], off offset:256
	global_load_dword v106, v[10:11], off offset:320
	global_load_dword v108, v[10:11], off offset:384
	global_load_dword v110, v[10:11], off offset:448
	global_load_dword v112, v[10:11], off offset:512
	global_load_dword v114, v[10:11], off offset:576
	global_load_dword v116, v[10:11], off offset:640
	global_load_dword v118, v[10:11], off offset:704
	global_load_dword v120, v[10:11], off offset:768
	global_load_dword v122, v[10:11], off offset:832
	global_load_dword v124, v[10:11], off offset:896
	global_load_dword v126, v[10:11], off offset:960
	v_lshl_add_u64 v[2:3], v[2:3], 0, s[10:11]
	v_lshl_add_u64 v[2:3], v[2:3], 0, s[10:11]
	v_lshl_add_u64 v[10:11], v[10:11], 0, s[96:97]
	v_lshl_add_u64 v[32:33], v[0:1], 0, 0
	v_lshl_add_u64 v[34:35], v[32:33], 0, s[100:101]
	v_lshl_add_u64 v[36:37], v[34:35], 0, s[100:101]
	v_lshl_add_u64 v[38:39], v[36:37], 0, s[100:101]
	v_lshl_add_u64 v[40:41], v[38:39], 0, s[100:101]
	v_lshl_add_u64 v[42:43], v[40:41], 0, s[100:101]
	v_lshl_add_u64 v[44:45], v[42:43], 0, s[100:101]
	v_lshl_add_u64 v[46:47], v[44:45], 0, s[100:101]
	v_lshl_add_u64 v[48:49], v[46:47], 0, s[100:101]
	v_lshl_add_u64 v[50:51], v[48:49], 0, s[100:101]
	v_lshl_add_u64 v[52:53], v[50:51], 0, s[100:101]
	v_lshl_add_u64 v[54:55], v[52:53], 0, s[100:101]
	v_lshl_add_u64 v[56:57], v[54:55], 0, s[100:101]
	v_lshl_add_u64 v[58:59], v[56:57], 0, s[100:101]
	v_lshl_add_u64 v[60:61], v[58:59], 0, s[100:101]
	v_lshl_add_u64 v[62:63], v[60:61], 0, s[100:101]
	s_waitcnt vmcnt(47)
; __device__ __forceinline__ int tid_op() { int t = threadIdx.x & 255; asm volatile("" : "+v"(t)); return t; }
; __device__ __forceinline__ int vb_op() { return (int)(blockIdx.x << 1) | sub_op(); }
; __device__ void ssd_scan_phase(const Params& p) {
;   const int nthr = p.nblk * 256;
;   for (int s = vb_op() * 256 + tid_op(); s < 131072; s += nthr) {
;     const int n2 = s & 63, pp = (s >> 6) & 63, h = (s >> 12) & 15, b = s >> 16;
;     const size_t off = (size_t)h * 8192 + pp * 128 + n2 * 2;
;     float c0 = 0.f, c1 = 0.f;
; #pragma unroll 8
;     for (int c = 0; c < 128; ++c) {
;       const size_t o = (size_t)(b * 128 + c) * 131072 + off;
;       const float2 st = *(const float2*)(p.states + o);
;       const float dec = p.cdecay[(b * 128 + c) * 16 + h];
;       *(u32*)(p.prev + o) = pack2(c0, c1);
;       c0 = c0 * dec + st.x;
;       c1 = c1 * dec + st.y;
;     }
;   }
; }
	v_cvt_pk_bf16_f32 v12, v4, v5
	global_store_dword v[32:33], v12, off
	v_pk_fma_f32 v[4:5], v[4:5], v[200:201], v[168:169] op_sel_hi:[1,0,1]
	s_nop 0
	s_waitcnt vmcnt(47)
	v_cvt_pk_bf16_f32 v13, v4, v5
	global_store_dword v[34:35], v13, off
	v_pk_fma_f32 v[4:5], v[4:5], v[202:203], v[170:171] op_sel_hi:[1,0,1]
	s_nop 0
	s_waitcnt vmcnt(47)
	v_cvt_pk_bf16_f32 v12, v4, v5
	global_store_dword v[36:37], v12, off
	v_pk_fma_f32 v[4:5], v[4:5], v[204:205], v[172:173] op_sel_hi:[1,0,1]
	s_nop 0
	s_waitcnt vmcnt(47)
	v_cvt_pk_bf16_f32 v13, v4, v5
	global_store_dword v[38:39], v13, off
	v_pk_fma_f32 v[4:5], v[4:5], v[206:207], v[174:175] op_sel_hi:[1,0,1]
	s_nop 0
	s_waitcnt vmcnt(47)
	v_cvt_pk_bf16_f32 v12, v4, v5
	global_store_dword v[40:41], v12, off
	v_pk_fma_f32 v[4:5], v[4:5], v[208:209], v[176:177] op_sel_hi:[1,0,1]
	s_nop 0
	s_waitcnt vmcnt(47)
	v_cvt_pk_bf16_f32 v13, v4, v5
	global_store_dword v[42:43], v13, off
	v_pk_fma_f32 v[4:5], v[4:5], v[210:211], v[178:179] op_sel_hi:[1,0,1]
	s_nop 0
	s_waitcnt vmcnt(47)
	v_cvt_pk_bf16_f32 v12, v4, v5
	global_store_dword v[44:45], v12, off
	v_pk_fma_f32 v[4:5], v[4:5], v[212:213], v[180:181] op_sel_hi:[1,0,1]
	s_nop 0
	s_waitcnt vmcnt(47)
	v_cvt_pk_bf16_f32 v13, v4, v5
	global_store_dword v[46:47], v13, off
	v_pk_fma_f32 v[4:5], v[4:5], v[214:215], v[182:183] op_sel_hi:[1,0,1]
	s_nop 0
	s_waitcnt vmcnt(47)
	v_cvt_pk_bf16_f32 v12, v4, v5
	global_store_dword v[48:49], v12, off
	v_pk_fma_f32 v[4:5], v[4:5], v[216:217], v[184:185] op_sel_hi:[1,0,1]
	s_nop 0
	s_waitcnt vmcnt(47)
	v_cvt_pk_bf16_f32 v13, v4, v5
	global_store_dword v[50:51], v13, off
	v_pk_fma_f32 v[4:5], v[4:5], v[218:219], v[186:187] op_sel_hi:[1,0,1]
	s_nop 0
	s_waitcnt vmcnt(47)
	v_cvt_pk_bf16_f32 v12, v4, v5
	global_store_dword v[52:53], v12, off
	v_pk_fma_f32 v[4:5], v[4:5], v[220:221], v[188:189] op_sel_hi:[1,0,1]
	s_nop 0
	s_waitcnt vmcnt(47)
	v_cvt_pk_bf16_f32 v13, v4, v5
	global_store_dword v[54:55], v13, off
	v_pk_fma_f32 v[4:5], v[4:5], v[222:223], v[190:191] op_sel_hi:[1,0,1]
	s_nop 0
	s_waitcnt vmcnt(47)
	v_cvt_pk_bf16_f32 v12, v4, v5
	global_store_dword v[56:57], v12, off
	v_pk_fma_f32 v[4:5], v[4:5], v[224:225], v[192:193] op_sel_hi:[1,0,1]
	s_nop 0
	s_waitcnt vmcnt(47)
	v_cvt_pk_bf16_f32 v13, v4, v5
	global_store_dword v[58:59], v13, off
	v_pk_fma_f32 v[4:5], v[4:5], v[226:227], v[194:195] op_sel_hi:[1,0,1]
	s_nop 0
	s_waitcnt vmcnt(47)
	v_cvt_pk_bf16_f32 v12, v4, v5
	global_store_dword v[60:61], v12, off
	v_pk_fma_f32 v[4:5], v[4:5], v[228:229], v[196:197] op_sel_hi:[1,0,1]
	s_nop 0
	s_waitcnt vmcnt(47)
	v_cvt_pk_bf16_f32 v13, v4, v5
	global_store_dword v[62:63], v13, off
	v_pk_fma_f32 v[4:5], v[4:5], v[230:231], v[198:199] op_sel_hi:[1,0,1]
	s_nop 0
	v_lshl_add_u64 v[0:1], v[0:1], 0, s[10:11]
	s_branch .Lscan_loop
.Lscan_last:
	v_lshl_add_u64 v[32:33], v[0:1], 0, 0
	v_lshl_add_u64 v[34:35], v[32:33], 0, s[100:101]
	v_lshl_add_u64 v[36:37], v[34:35], 0, s[100:101]
	v_lshl_add_u64 v[38:39], v[36:37], 0, s[100:101]
	v_lshl_add_u64 v[40:41], v[38:39], 0, s[100:101]
	v_lshl_add_u64 v[42:43], v[40:41], 0, s[100:101]
	v_lshl_add_u64 v[44:45], v[42:43], 0, s[100:101]
	v_lshl_add_u64 v[46:47], v[44:45], 0, s[100:101]
	v_lshl_add_u64 v[48:49], v[46:47], 0, s[100:101]
	v_lshl_add_u64 v[50:51], v[48:49], 0, s[100:101]
	v_lshl_add_u64 v[52:53], v[50:51], 0, s[100:101]
	v_lshl_add_u64 v[54:55], v[52:53], 0, s[100:101]
	v_lshl_add_u64 v[56:57], v[54:55], 0, s[100:101]
	v_lshl_add_u64 v[58:59], v[56:57], 0, s[100:101]
	v_lshl_add_u64 v[60:61], v[58:59], 0, s[100:101]
	v_lshl_add_u64 v[62:63], v[60:61], 0, s[100:101]
	s_waitcnt vmcnt(15)
	v_cvt_pk_bf16_f32 v12, v4, v5
	global_store_dword v[32:33], v12, off
	v_pk_fma_f32 v[4:5], v[4:5], v[200:201], v[168:169] op_sel_hi:[1,0,1]
	s_nop 0
	s_waitcnt vmcnt(15)
	v_cvt_pk_bf16_f32 v13, v4, v5
	global_store_dword v[34:35], v13, off
	v_pk_fma_f32 v[4:5], v[4:5], v[202:203], v[170:171] op_sel_hi:[1,0,1]
	s_nop 0
	s_waitcnt vmcnt(15)
	v_cvt_pk_bf16_f32 v12, v4, v5
	global_store_dword v[36:37], v12, off
	v_pk_fma_f32 v[4:5], v[4:5], v[204:205], v[172:173] op_sel_hi:[1,0,1]
	s_nop 0
	s_waitcnt vmcnt(15)
	v_cvt_pk_bf16_f32 v13, v4, v5
	global_store_dword v[38:39], v13, off
	v_pk_fma_f32 v[4:5], v[4:5], v[206:207], v[174:175] op_sel_hi:[1,0,1]
	s_nop 0
	s_waitcnt vmcnt(15)
	v_cvt_pk_bf16_f32 v12, v4, v5
	global_store_dword v[40:41], v12, off
	v_pk_fma_f32 v[4:5], v[4:5], v[208:209], v[176:177] op_sel_hi:[1,0,1]
	s_nop 0
	s_waitcnt vmcnt(15)
	v_cvt_pk_bf16_f32 v13, v4, v5
	global_store_dword v[42:43], v13, off
	v_pk_fma_f32 v[4:5], v[4:5], v[210:211], v[178:179] op_sel_hi:[1,0,1]
	s_nop 0
	s_waitcnt vmcnt(15)
	v_cvt_pk_bf16_f32 v12, v4, v5
	global_store_dword v[44:45], v12, off
	v_pk_fma_f32 v[4:5], v[4:5], v[212:213], v[180:181] op_sel_hi:[1,0,1]
	s_nop 0
	s_waitcnt vmcnt(15)
	v_cvt_pk_bf16_f32 v13, v4, v5
	global_store_dword v[46:47], v13, off
	v_pk_fma_f32 v[4:5], v[4:5], v[214:215], v[182:183] op_sel_hi:[1,0,1]
	s_nop 0
	s_waitcnt vmcnt(15)
	v_cvt_pk_bf16_f32 v12, v4, v5
	global_store_dword v[48:49], v12, off
	v_pk_fma_f32 v[4:5], v[4:5], v[216:217], v[184:185] op_sel_hi:[1,0,1]
	s_nop 0
	s_waitcnt vmcnt(15)
	v_cvt_pk_bf16_f32 v13, v4, v5
	global_store_dword v[50:51], v13, off
	v_pk_fma_f32 v[4:5], v[4:5], v[218:219], v[186:187] op_sel_hi:[1,0,1]
	s_nop 0
	s_waitcnt vmcnt(15)
	v_cvt_pk_bf16_f32 v12, v4, v5
	global_store_dword v[52:53], v12, off
	v_pk_fma_f32 v[4:5], v[4:5], v[220:221], v[188:189] op_sel_hi:[1,0,1]
	s_nop 0
	s_waitcnt vmcnt(15)
	v_cvt_pk_bf16_f32 v13, v4, v5
	global_store_dword v[54:55], v13, off
	v_pk_fma_f32 v[4:5], v[4:5], v[222:223], v[190:191] op_sel_hi:[1,0,1]
	s_nop 0
	s_waitcnt vmcnt(15)
	v_cvt_pk_bf16_f32 v12, v4, v5
	global_store_dword v[56:57], v12, off
	v_pk_fma_f32 v[4:5], v[4:5], v[224:225], v[192:193] op_sel_hi:[1,0,1]
	s_nop 0
	s_waitcnt vmcnt(15)
	v_cvt_pk_bf16_f32 v13, v4, v5
	global_store_dword v[58:59], v13, off
	v_pk_fma_f32 v[4:5], v[4:5], v[226:227], v[194:195] op_sel_hi:[1,0,1]
	s_nop 0
	s_waitcnt vmcnt(15)
	v_cvt_pk_bf16_f32 v12, v4, v5
	global_store_dword v[60:61], v12, off
	v_pk_fma_f32 v[4:5], v[4:5], v[228:229], v[196:197] op_sel_hi:[1,0,1]
	s_nop 0
	s_waitcnt vmcnt(15)
	v_cvt_pk_bf16_f32 v13, v4, v5
	global_store_dword v[62:63], v13, off
	v_pk_fma_f32 v[4:5], v[4:5], v[230:231], v[198:199] op_sel_hi:[1,0,1]
	s_nop 0
	v_lshl_add_u64 v[0:1], v[0:1], 0, s[10:11]
	v_add_u32_e32 v6, s12, v6
	v_cmp_lt_i32_e32 vcc, s20, v6
	s_or_b64 s[6:7], vcc, s[6:7]
	v_add_u32_e32 v7, s13, v7
	s_andn2_b64 exec, exec, s[6:7]
	s_cbranch_execnz .LBB0_392
